# FFN gate-up balance: P7's idle sixth-round slots compute 128 tiles of the second row half (H of the second half moved to ws+168MiB so nothing P8 reads is overwritten); P9 then has 1280 tiles = 5 full
# speedup vs baseline: 1.0110x; 1.0110x over previous
; #define PG8_STAGE(bufoff, gbase, voff) do { _Pragma("unroll") for (int _i = 0; _i < 2; ++_i) \
;         __builtin_amdgcn_global_load_lds((const unsigned*)((const char*)(gbase) + (voff)[_i]), (PG8_LAS unsigned*)(lds + (bufoff) + ldsw + _i * 8192), 16, 0, 0); } while (0)
; #define PG8_WAIT_V(n) asm volatile("s_waitcnt vmcnt(" #n ")" ::: "memory")
; #define PG8_BAR __builtin_amdgcn_s_barrier()
; template <class Epi, class Sched, bool ALIGN_EPI = false, bool SP2 = false>
; __device__ __forceinline__ void gemm_phase(PG8_LAS unsigned char* lds, const Gemm g, const Sched& S, const Epi& E) {
;     ...
;         PG8_STAGE(PG8_SB(1, 0), cB + kstep, voffB); PG8_STAGE(PG8_SA(1, 0), cA + kstep, voffA); PG8_STAGE(PG8_SB(1, 1), cB + hstep + kstep, voffB);
;         PG8_WAIT_V(6); PG8_BAR;
;     } else {
;         PG8_STAGE(PG8_SB(0, 0), cB, voffB); PG8_STAGE(PG8_SA(0, 0), cA, voffA); PG8_STAGE(PG8_SB(0, 1), cB + hstep, voffB); PG8_STAGE(PG8_SA(0, 1), cA + hstep, voffA);
;         if (wr == 1) PG8_BAR;
;         PG8_WAIT_V(4); PG8_BAR;
;         PG8_STAGE(PG8_SB(1, 0), cB + kstep, voffB); PG8_STAGE(PG8_SA(1, 0), cA + kstep, voffA); PG8_STAGE(PG8_SB(1, 1), cB + hstep + kstep, voffB);
;         PG8_WAIT_V(6); PG8_BAR;
.LBB0_1481:
	s_lshl_b32 s1, s9, 5
	s_mov_b64 s[16:17], 0x80
	s_and_b32 s9, s1, 0x60
	s_add_i32 m0, s31, 0x18000
	v_lshl_add_u64 v[6:7], v[6:7], 0, s[16:17]
	s_lshl_b32 s18, s8, 13
	s_lshl_b32 s19, s9, 7
	global_load_lds_dwordx4 v[6:7], off
	v_lshl_add_u64 v[4:5], v[4:5], 0, s[16:17]
	s_add_i32 m0, s31, 0x1a000
	s_add_i32 s38, s31, 0x8000
	s_add_i32 s39, s31, 0xa000
	global_load_lds_dwordx4 v[4:5], off
	v_lshl_add_u64 v[0:1], v[0:1], 0, s[16:17]
	s_mov_b32 m0, s38
	s_add_u32 s10, s6, 0x40080
	global_load_lds_dwordx4 v[0:1], off
	v_lshl_add_u64 v[0:1], v[2:3], 0, s[16:17]
	s_mov_b32 m0, s39
	s_addc_u32 s11, s7, 0
	global_load_lds_dwordx4 v[0:1], off
	s_add_i32 m0, s31, 0x1c000
	v_lshl_add_u64 v[0:1], s[10:11], 0, v[132:133]
	global_load_lds_dwordx4 v[0:1], off
	v_lshl_add_u64 v[0:1], s[10:11], 0, v[128:129]
	s_add_i32 m0, s31, 0x1e000
	s_sext_i32_i16 s1, s2
	global_load_lds_dwordx4 v[0:1], off
	s_waitcnt vmcnt(8)
	s_barrier
	v_and_b32_e32 v0, 15, v150
	v_lshlrev_b32_e32 v1, 1, v11
	v_lshlrev_b32_e32 v2, 2, v150
	v_lshlrev_b32_e32 v3, 6, v150
	s_movk_i32 s2, 0x3c0
	v_lshl_or_b32 v149, s8, 6, v0
	v_lshl_or_b32 v0, v0, 6, v1
	v_and_b32_e32 v2, 32, v2
	v_and_or_b32 v1, v3, s2, v1
	v_bitop3_b32 v151, s19, v1, v2 bitop3:0xf6
	v_lshlrev_b32_e32 v1, 8, v150
	v_bitop3_b32 v0, v0, s18, v2 bitop3:0xde
	v_and_b32_e32 v1, 0x38000, v1
	v_lshlrev_b32_e32 v2, 11, v12
	v_or3_b32 v1, v9, v1, v2
	v_add_u32_e32 v136, v1, v10
	v_lshlrev_b32_e32 v1, 4, v8
	s_waitcnt vmcnt(6)
	s_cmpk_lt_u32 s3, 0x100
	v_and_b32_e32 v1, 0x78000, v1
	s_cselect_b64 s[18:19], -1, 0
	v_or3_b32 v1, v9, v1, v2
	s_add_i32 s41, 0, 0x10000
	s_add_i32 s42, 0, 0x14000
	s_ashr_i32 s40, s89, 31
	v_or_b32_e32 v154, s9, v11
	v_mov_b32_e32 v137, v133
	v_add_u32_e32 v138, v1, v10
	v_mov_b32_e32 v139, v133
	v_mov_b64_e32 v[140:141], 0x600
	v_mov_b64_e32 v[142:143], 0x5ff
	v_add_u32_e32 v155, s41, v151
	v_add_u32_e32 v156, s42, v151
	v_add_u32_e32 v157, 0, v0
	v_mov_b32_e32 v158, 0x358637bd
	s_mov_b32 s43, 0x800000
	s_movk_i32 s44, 0x1600
	s_barrier
	s_branch .LBB0_1484

;     __host__ __device__ bool next(int i, Unit& u) const {
;         const long L = (long)i * G + c; if (L >= nwg) return false;
;         int wgid = (int)L; { const int q = nwg / NXCD, r = nwg % NXCD, xcd = wgid % NXCD, off = wgid / NXCD; wgid = (xcd < r ? xcd * (q + 1) : r * (q + 1) + (xcd - r) * q) + off; }
;         const int nig = WGM * nN, gid = wgid / nig, fm = gid * WGM, gsz = (nM - fm) < WGM ? (nM - fm) : WGM;
;         u.pm = fm + ((wgid % nig) % gsz); u.pn = (wgid % nig) / gsz; return true;
;     }
.LBB0_1484:
	s_add_i32 s37, s37, 1
	s_mul_i32 s2, s37, s40
	s_mul_hi_u32 s3, s37, s89
	s_add_i32 s3, s3, s2
	s_mul_i32 s2, s37, s89
	s_add_u32 s8, s2, s33
	s_addc_u32 s9, s3, s29
	v_cmp_gt_i64_e32 vcc, s[8:9], v[142:143]
	v_cmp_lt_i64_e64 s[2:3], s[8:9], v[140:141]
	s_cbranch_vccnz .LBB0_1486
	s_ashr_i32 s9, s8, 31
	s_lshr_b32 s9, s9, 29
	s_add_i32 s9, s8, s9
	s_ashr_i32 s10, s9, 3
	s_and_b32 s9, s9, -8
	s_sub_i32 s8, s8, s9
	s_cmp_lt_i32 s8, 0
	s_cselect_b32 s9, s30, 0xb0
	s_mul_i32 s8, s8, s9
	s_add_i32 s8, s8, s10
	s_mov_b32 s100, 0
	s_cmpk_lt_i32 s10, 0xb0
	s_cbranch_scc1 .Lp7_dec_done
	s_and_b32 s98, s33, 7
	s_sub_i32 s99, s10, 0xb0
	s_mov_b32 s100, 64
	s_cmp_gt_u32 s98, 1
	s_cbranch_scc1 .Lp7_dec_x2
	s_lshl_b32 s98, s98, 1
	s_lshr_b32 s8, s99, 3
	s_add_i32 s98, s98, s8
	s_add_i32 s98, s98, 2
	s_and_b32 s99, s99, 7
	s_addk_i32 s99, 0x98
	s_branch .Lp7_dec_mk
	s_nop 0
	s_nop 0
	s_nop 0
	s_nop 0
	s_nop 0
	s_nop 0
	s_nop 0
	s_nop 0
	s_nop 0
	s_nop 0
	s_nop 0
.Lp7_dec_x2:
	s_addk_i32 s99, 0xa0
.Lp7_dec_mk:
	s_mul_i32 s8, s98, 0xb0
	s_add_i32 s8, s8, s99
.Lp7_dec_done:
	s_mul_hi_i32 s9, s8, 0x2e8ba2e9
	s_lshr_b32 s10, s9, 31
	s_ashr_i32 s9, s9, 5
	s_add_i32 s9, s9, s10
	s_lshl_b32 s10, s9, 3
	s_sub_i32 s11, 64, s10
	s_min_i32 s11, s11, 8
	s_abs_i32 s20, s11
	v_cvt_f32_u32_e32 v0, s20
	s_sub_i32 s22, 0, s20
	s_mulk_i32 s9, 0xb0
	s_sub_i32 s8, s8, s9
	v_rcp_iflag_f32_e32 v0, v0
	s_abs_i32 s9, s8
	s_xor_b32 s21, s8, s11
	s_ashr_i32 s21, s21, 31
	v_mul_f32_e32 v0, 0x4f7ffffe, v0
	v_cvt_u32_f32_e32 v0, v0
	s_nop 0
	v_readfirstlane_b32 s23, v0
	s_mul_i32 s22, s22, s23
	s_mul_hi_u32 s22, s23, s22
	s_add_i32 s23, s23, s22
	s_mul_hi_u32 s22, s9, s23
	s_mul_i32 s23, s22, s20
	s_sub_i32 s9, s9, s23
	s_add_i32 s24, s22, 1
	s_sub_i32 s23, s9, s20
	s_cmp_ge_u32 s9, s20
	s_cselect_b32 s22, s24, s22
	s_cselect_b32 s9, s23, s9
	s_add_i32 s23, s22, 1
	s_cmp_ge_u32 s9, s20
	s_cselect_b32 s9, s23, s22
	s_xor_b32 s9, s9, s21
	s_sub_i32 s20, s9, s21
	s_mul_i32 s9, s20, s11
	s_sub_i32 s8, s8, s9
	s_add_i32 s22, s10, s8
	s_add_i32 s22, s22, s100

; DI unsigned pk2(float lo, float hi) { f32x2_t v = {lo, hi}; bf16x2_t b = __builtin_convertvector(v, bf16x2_t); return __builtin_bit_cast(unsigned, b); }
; DI float sigmoidf_(float x) { return 1.0f / (1.0f + __expf(-x)); }
;     DI void operator()(AccRef acc, const Unit& u, int wr, int wc, int fr, int fq) const {
;         const int row0 = u.pm * BM + wr * 64 + fr, col0 = u.pn * 128 + wc * 32 + 8 * fq;
; #pragma unroll
;         for (int ai = 0; ai < 2; ++ai)
; #pragma unroll
;             for (int m = 0; m < 4; ++m) {
;                 const int row = row0 + ai * HALF + m * 16; const float rs = rsqrtf(SS1[row] * (1.0f / DM) + EPSN);
;                 float h[8];
; #pragma unroll
;                 for (int n = 0; n < 2; ++n)
; #pragma unroll
;                     for (int e = 0; e < 4; ++e) { const float g = acc[ai][0][m][n][e] * rs, up = acc[ai][1][m][n][e] * rs; h[4 * n + e] = g * sigmoidf_(g) * up; }
;                 u32x4 w; w.x = pk2(h[0], h[1]); w.y = pk2(h[2], h[3]); w.z = pk2(h[4], h[5]); w.w = pk2(h[6], h[7]);
;                 *(u32x4*)(H + (size_t)row * DFF + col0) = w;
;             }
.LBB0_1490:
	v_lshl_add_u32 v144, s0, 8, v149
	v_ashrrev_i32_e32 v145, 31, v144
	v_lshl_add_u64 v[146:147], v[144:145], 2, s[46:47]
	global_load_dword v145, v[146:147], off
	global_load_dword v248, v[146:147], off offset:64
	global_load_dword v249, v[146:147], off offset:128
	global_load_dword v250, v[146:147], off offset:192
	global_load_dword v251, v[146:147], off offset:512
	global_load_dword v252, v[146:147], off offset:576
	global_load_dword v253, v[146:147], off offset:640
	global_load_dword v254, v[146:147], off offset:704
	s_waitcnt vmcnt(0)
	v_fmamk_f32 v145, v145, 0x3a800000, v158
	v_mul_f32_e32 v152, 0x4b800000, v145
	v_cmp_gt_f32_e32 vcc, s43, v145
	s_nop 1
	v_cndmask_b32_e32 v145, v145, v152, vcc
	v_rsq_f32_e32 v145, v145
	v_lshl_or_b32 v152, s1, 7, v154
	v_ashrrev_i32_e32 v153, 31, v152
	v_mul_f32_e32 v159, 0x45800000, v145
	v_cndmask_b32_e32 v160, v145, v159, vcc
	v_pk_mul_f32 v[124:125], v[124:125], v[160:161] op_sel_hi:[1,0]
	v_pk_mul_f32 v[126:127], v[126:127], v[160:161] op_sel_hi:[1,0]
	v_mul_f32_e32 v145, 0xbfb8aa3b, v124
	v_mul_f32_e32 v159, 0xbfb8aa3b, v125
	v_exp_f32_e32 v162, v145
	v_exp_f32_e32 v163, v159
	v_pk_mul_f32 v[120:121], v[120:121], v[160:161] op_sel_hi:[1,0]
	v_pk_mul_f32 v[122:123], v[122:123], v[160:161] op_sel_hi:[1,0]
	v_pk_mul_f32 v[116:117], v[116:117], v[160:161] op_sel_hi:[1,0]
	v_mul_f32_e32 v161, 0xbfb8aa3b, v126
	v_mul_f32_e32 v165, 0xbfb8aa3b, v127
	v_exp_f32_e32 v164, v161
	v_exp_f32_e32 v165, v165
	v_pk_add_f32 v[162:163], v[162:163], 1.0 op_sel_hi:[1,0]
	v_pk_mul_f32 v[112:113], v[112:113], v[160:161] op_sel_hi:[1,0]
	v_pk_add_f32 v[164:165], v[164:165], 1.0 op_sel_hi:[1,0]
	v_mul_f32_e32 v166, 0xbfb8aa3b, v116
	v_mul_f32_e32 v167, 0xbfb8aa3b, v117
	v_exp_f32_e32 v166, v166
	v_exp_f32_e32 v167, v167
	s_nop 0
	v_pk_add_f32 v[166:167], v[166:167], 1.0 op_sel_hi:[1,0]
	v_rcp_f32_e32 v163, v163
	v_rcp_f32_e32 v162, v162
	s_nop 0
	v_pk_mul_f32 v[124:125], v[124:125], v[162:163]
	v_rcp_f32_e32 v163, v165
	v_rcp_f32_e32 v162, v164
	v_pk_mul_f32 v[120:121], v[120:121], v[124:125]
	v_pk_mul_f32 v[124:125], v[126:127], v[162:163]
	v_pk_mul_f32 v[118:119], v[118:119], v[160:161] op_sel_hi:[1,0]
	v_pk_mul_f32 v[122:123], v[122:123], v[124:125]
	v_mul_f32_e32 v124, 0xbfb8aa3b, v118
	v_mul_f32_e32 v125, 0xbfb8aa3b, v119
	v_exp_f32_e32 v124, v124
	v_exp_f32_e32 v125, v125
	s_nop 0
	v_pk_add_f32 v[124:125], v[124:125], 1.0 op_sel_hi:[1,0]
	v_rcp_f32_e32 v127, v167
	v_rcp_f32_e32 v126, v166
	s_nop 0
	v_pk_mul_f32 v[116:117], v[116:117], v[126:127]
	v_pk_mul_f32 v[114:115], v[114:115], v[160:161] op_sel_hi:[1,0]
	v_pk_mul_f32 v[112:113], v[112:113], v[116:117]
	v_rcp_f32_e32 v117, v125
	v_rcp_f32_e32 v116, v124
	s_nop 0
	v_pk_mul_f32 v[116:117], v[118:119], v[116:117]
	v_cvt_pk_bf16_f32 v118, v112, v113
	v_pk_mul_f32 v[114:115], v[114:115], v[116:117]
	s_cmp_gt_i32 s0, 63
	s_cselect_b32 s98, 0x1000000, 0
	s_sub_u32 s98, s48, s98
	s_subb_u32 s99, s49, 0
	v_mov_b64_e32 v[112:113], s[98:99]
	v_cvt_pk_bf16_f32 v116, v120, v121
	v_cvt_pk_bf16_f32 v119, v114, v115
	v_mad_i64_i32 v[120:121], s[0:1], v144, s44, v[112:113]
	v_lshlrev_b64 v[114:115], 1, v[152:153]
	v_cvt_pk_bf16_f32 v117, v122, v123
	v_lshl_add_u64 v[120:121], v[120:121], 0, v[114:115]
	global_store_dwordx4 v[120:121], v[116:119], off
	s_nop 1
	v_or_b32_e32 v116, 16, v144
	v_ashrrev_i32_e32 v117, 31, v116
	v_lshl_add_u64 v[118:119], v[116:117], 2, s[46:47]
	s_nop 0
	s_nop 0
	v_fmamk_f32 v117, v248, 0x3a800000, v158
	v_mul_f32_e32 v118, 0x4b800000, v117
	v_cmp_gt_f32_e32 vcc, s43, v117
	s_nop 1
	v_cndmask_b32_e32 v117, v117, v118, vcc
	v_rsq_f32_e32 v117, v117
	s_nop 0
	v_mul_f32_e32 v118, 0x45800000, v117
	v_cndmask_b32_e32 v118, v117, v118, vcc
	v_pk_mul_f32 v[108:109], v[108:109], v[118:119] op_sel_hi:[1,0]
	v_pk_mul_f32 v[110:111], v[110:111], v[118:119] op_sel_hi:[1,0]
	v_mul_f32_e32 v117, 0xbfb8aa3b, v108
	v_mul_f32_e32 v119, 0xbfb8aa3b, v109
	v_exp_f32_e32 v120, v117
	v_exp_f32_e32 v121, v119
	v_mul_f32_e32 v122, 0xbfb8aa3b, v110
	v_mul_f32_e32 v123, 0xbfb8aa3b, v111
	v_exp_f32_e32 v122, v122
	v_pk_add_f32 v[120:121], v[120:121], 1.0 op_sel_hi:[1,0]
	v_exp_f32_e32 v123, v123
	s_nop 0
	v_pk_add_f32 v[122:123], v[122:123], 1.0 op_sel_hi:[1,0]
	v_pk_mul_f32 v[104:105], v[104:105], v[118:119] op_sel_hi:[1,0]
	v_pk_mul_f32 v[106:107], v[106:107], v[118:119] op_sel_hi:[1,0]
	v_rcp_f32_e32 v121, v121
	v_rcp_f32_e32 v120, v120
	s_nop 0
	v_pk_mul_f32 v[108:109], v[108:109], v[120:121]
	v_pk_mul_f32 v[104:105], v[104:105], v[108:109]
	v_rcp_f32_e32 v109, v123
	v_pk_mul_f32 v[100:101], v[100:101], v[118:119] op_sel_hi:[1,0]
	v_mul_f32_e32 v117, 0xbfb8aa3b, v100
	v_exp_f32_e32 v120, v117
	v_mul_f32_e32 v117, 0xbfb8aa3b, v101
	v_exp_f32_e32 v121, v117
	v_rcp_f32_e32 v108, v122
	s_nop 0
	v_pk_mul_f32 v[108:109], v[110:111], v[108:109]
	v_pk_add_f32 v[120:121], v[120:121], 1.0 op_sel_hi:[1,0]
	v_pk_mul_f32 v[106:107], v[106:107], v[108:109]
	s_nop 0
	v_pk_mul_f32 v[96:97], v[96:97], v[118:119] op_sel_hi:[1,0]
	v_rcp_f32_e32 v109, v121
	v_pk_mul_f32 v[102:103], v[102:103], v[118:119] op_sel_hi:[1,0]
	v_mul_f32_e32 v110, 0xbfb8aa3b, v102
	v_mul_f32_e32 v111, 0xbfb8aa3b, v103
	v_exp_f32_e32 v110, v110
	v_exp_f32_e32 v111, v111
	v_rcp_f32_e32 v108, v120
	s_nop 0
	v_pk_mul_f32 v[100:101], v[100:101], v[108:109]
	v_pk_add_f32 v[110:111], v[110:111], 1.0 op_sel_hi:[1,0]
	v_pk_mul_f32 v[100:101], v[96:97], v[100:101]
	s_nop 0
	v_pk_mul_f32 v[96:97], v[98:99], v[118:119] op_sel_hi:[1,0]
	v_rcp_f32_e32 v99, v111
	v_rcp_f32_e32 v98, v110
	s_nop 0
	v_pk_mul_f32 v[98:99], v[102:103], v[98:99]
	s_nop 0
	v_pk_mul_f32 v[102:103], v[96:97], v[98:99]
	v_cvt_pk_bf16_f32 v98, v100, v101
; DI unsigned pk2(float lo, float hi) { f32x2_t v = {lo, hi}; bf16x2_t b = __builtin_convertvector(v, bf16x2_t); return __builtin_bit_cast(unsigned, b); }
; DI float sigmoidf_(float x) { return 1.0f / (1.0f + __expf(-x)); }
;     DI void operator()(AccRef acc, const Unit& u, int wr, int wc, int fr, int fq) const {
;     ...
;         for (int ai = 0; ai < 2; ++ai)
; #pragma unroll
;             for (int m = 0; m < 4; ++m) {
;                 const int row = row0 + ai * HALF + m * 16; const float rs = rsqrtf(SS1[row] * (1.0f / DM) + EPSN);
;                 float h[8];
; #pragma unroll
;                 for (int n = 0; n < 2; ++n)
; #pragma unroll
;                     for (int e = 0; e < 4; ++e) { const float g = acc[ai][0][m][n][e] * rs, up = acc[ai][1][m][n][e] * rs; h[4 * n + e] = g * sigmoidf_(g) * up; }
;                 u32x4 w; w.x = pk2(h[0], h[1]); w.y = pk2(h[2], h[3]); w.z = pk2(h[4], h[5]); w.w = pk2(h[6], h[7]);
;                 *(u32x4*)(H + (size_t)row * DFF + col0) = w;
;             }
	v_mad_i64_i32 v[100:101], s[0:1], v116, s44, v[112:113]
	v_cvt_pk_bf16_f32 v96, v104, v105
	v_cvt_pk_bf16_f32 v97, v106, v107
	v_cvt_pk_bf16_f32 v99, v102, v103
	v_lshl_add_u64 v[100:101], v[100:101], 0, v[114:115]
	global_store_dwordx4 v[100:101], v[96:99], off
	s_nop 1
	v_or_b32_e32 v96, 32, v144
	v_ashrrev_i32_e32 v97, 31, v96
	v_lshl_add_u64 v[98:99], v[96:97], 2, s[46:47]
	s_nop 0
	s_nop 0
	v_fmamk_f32 v97, v249, 0x3a800000, v158
	v_mul_f32_e32 v98, 0x4b800000, v97
	v_cmp_gt_f32_e32 vcc, s43, v97
	s_nop 1
	v_cndmask_b32_e32 v97, v97, v98, vcc
	v_rsq_f32_e32 v97, v97
	s_nop 0
	v_mul_f32_e32 v98, 0x45800000, v97
	v_cndmask_b32_e32 v98, v97, v98, vcc
	v_pk_mul_f32 v[92:93], v[92:93], v[98:99] op_sel_hi:[1,0]
	s_nop 0
	v_mul_f32_e32 v97, 0xbfb8aa3b, v92
	v_exp_f32_e32 v100, v97
	v_mul_f32_e32 v97, 0xbfb8aa3b, v93
	v_exp_f32_e32 v101, v97
	s_nop 0
	v_pk_add_f32 v[100:101], v[100:101], 1.0 op_sel_hi:[1,0]
	s_nop 0
	s_nop 0
	v_pk_mul_f32 v[88:89], v[88:89], v[98:99] op_sel_hi:[1,0]
	v_rcp_f32_e32 v101, v101
	v_pk_mul_f32 v[94:95], v[94:95], v[98:99] op_sel_hi:[1,0]
	v_mul_f32_e32 v102, 0xbfb8aa3b, v94
	v_mul_f32_e32 v103, 0xbfb8aa3b, v95
	v_exp_f32_e32 v102, v102
	v_exp_f32_e32 v103, v103
	v_rcp_f32_e32 v100, v100
	s_nop 0
	v_pk_mul_f32 v[92:93], v[92:93], v[100:101]
	v_pk_add_f32 v[102:103], v[102:103], 1.0 op_sel_hi:[1,0]
	v_pk_mul_f32 v[88:89], v[88:89], v[92:93]
	s_nop 0
	v_pk_mul_f32 v[90:91], v[90:91], v[98:99] op_sel_hi:[1,0]
	v_rcp_f32_e32 v93, v103
	v_pk_mul_f32 v[84:85], v[84:85], v[98:99] op_sel_hi:[1,0]
	v_mul_f32_e32 v97, 0xbfb8aa3b, v84
	v_exp_f32_e32 v100, v97
	v_mul_f32_e32 v97, 0xbfb8aa3b, v85
	v_exp_f32_e32 v101, v97
	v_rcp_f32_e32 v92, v102
	s_nop 0
	v_pk_mul_f32 v[92:93], v[94:95], v[92:93]
	v_pk_add_f32 v[100:101], v[100:101], 1.0 op_sel_hi:[1,0]
	v_pk_mul_f32 v[90:91], v[90:91], v[92:93]
	s_nop 0
	v_pk_mul_f32 v[80:81], v[80:81], v[98:99] op_sel_hi:[1,0]
	v_rcp_f32_e32 v93, v101
	v_pk_mul_f32 v[86:87], v[86:87], v[98:99] op_sel_hi:[1,0]
	v_mul_f32_e32 v94, 0xbfb8aa3b, v86
	v_mul_f32_e32 v95, 0xbfb8aa3b, v87
	v_exp_f32_e32 v94, v94
	v_exp_f32_e32 v95, v95
	v_rcp_f32_e32 v92, v100
	s_nop 0
	v_pk_mul_f32 v[84:85], v[84:85], v[92:93]
	v_pk_add_f32 v[94:95], v[94:95], 1.0 op_sel_hi:[1,0]
	v_pk_mul_f32 v[84:85], v[80:81], v[84:85]
	s_nop 0
	v_pk_mul_f32 v[80:81], v[82:83], v[98:99] op_sel_hi:[1,0]
	v_rcp_f32_e32 v83, v95
	v_rcp_f32_e32 v82, v94
	s_nop 0
	v_pk_mul_f32 v[82:83], v[86:87], v[82:83]
	s_nop 0
	v_pk_mul_f32 v[86:87], v[80:81], v[82:83]
	v_cvt_pk_bf16_f32 v82, v84, v85
	v_mad_i64_i32 v[84:85], s[0:1], v96, s44, v[112:113]
	v_cvt_pk_bf16_f32 v80, v88, v89
	v_cvt_pk_bf16_f32 v81, v90, v91
	v_cvt_pk_bf16_f32 v83, v86, v87
	v_lshl_add_u64 v[84:85], v[84:85], 0, v[114:115]
	global_store_dwordx4 v[84:85], v[80:83], off
	s_nop 1
	v_or_b32_e32 v80, 48, v144
	v_ashrrev_i32_e32 v81, 31, v80
	v_lshl_add_u64 v[82:83], v[80:81], 2, s[46:47]
	s_nop 0
	s_nop 0
	v_fmamk_f32 v81, v250, 0x3a800000, v158
	v_mul_f32_e32 v82, 0x4b800000, v81
	v_cmp_gt_f32_e32 vcc, s43, v81
	s_nop 1
	v_cndmask_b32_e32 v81, v81, v82, vcc
	v_rsq_f32_e32 v81, v81
	s_nop 0
	v_mul_f32_e32 v82, 0x45800000, v81
	v_cndmask_b32_e32 v82, v81, v82, vcc
	v_pk_mul_f32 v[76:77], v[76:77], v[82:83] op_sel_hi:[1,0]
	s_nop 0
	v_mul_f32_e32 v81, 0xbfb8aa3b, v76
	v_exp_f32_e32 v84, v81
	v_mul_f32_e32 v81, 0xbfb8aa3b, v77
	v_exp_f32_e32 v85, v81
	s_nop 0
	v_pk_add_f32 v[84:85], v[84:85], 1.0 op_sel_hi:[1,0]
	s_nop 0
	s_nop 0
	v_pk_mul_f32 v[72:73], v[72:73], v[82:83] op_sel_hi:[1,0]
	v_rcp_f32_e32 v85, v85
	v_pk_mul_f32 v[78:79], v[78:79], v[82:83] op_sel_hi:[1,0]
	v_mul_f32_e32 v86, 0xbfb8aa3b, v78
	v_mul_f32_e32 v87, 0xbfb8aa3b, v79
	v_exp_f32_e32 v86, v86
	v_exp_f32_e32 v87, v87
	v_rcp_f32_e32 v84, v84
	s_nop 0
	v_pk_mul_f32 v[76:77], v[76:77], v[84:85]
	v_pk_add_f32 v[86:87], v[86:87], 1.0 op_sel_hi:[1,0]
	v_pk_mul_f32 v[72:73], v[72:73], v[76:77]
	s_nop 0
	v_pk_mul_f32 v[74:75], v[74:75], v[82:83] op_sel_hi:[1,0]
	v_rcp_f32_e32 v77, v87
	v_pk_mul_f32 v[68:69], v[68:69], v[82:83] op_sel_hi:[1,0]
	v_mul_f32_e32 v81, 0xbfb8aa3b, v68
	v_exp_f32_e32 v84, v81
	v_mul_f32_e32 v81, 0xbfb8aa3b, v69
	v_exp_f32_e32 v85, v81
	v_rcp_f32_e32 v76, v86
	s_nop 0
	v_pk_mul_f32 v[76:77], v[78:79], v[76:77]
	v_pk_add_f32 v[84:85], v[84:85], 1.0 op_sel_hi:[1,0]
	v_pk_mul_f32 v[74:75], v[74:75], v[76:77]
	s_nop 0
	v_pk_mul_f32 v[64:65], v[64:65], v[82:83] op_sel_hi:[1,0]
	v_rcp_f32_e32 v77, v85
	v_pk_mul_f32 v[70:71], v[70:71], v[82:83] op_sel_hi:[1,0]
	v_mul_f32_e32 v78, 0xbfb8aa3b, v70
	v_mul_f32_e32 v79, 0xbfb8aa3b, v71
	v_exp_f32_e32 v78, v78
	v_exp_f32_e32 v79, v79
	v_rcp_f32_e32 v76, v84
	s_nop 0
	v_pk_mul_f32 v[68:69], v[68:69], v[76:77]
	v_pk_add_f32 v[78:79], v[78:79], 1.0 op_sel_hi:[1,0]
	v_pk_mul_f32 v[68:69], v[64:65], v[68:69]
	s_nop 0
	v_pk_mul_f32 v[64:65], v[66:67], v[82:83] op_sel_hi:[1,0]
	v_rcp_f32_e32 v67, v79
	v_rcp_f32_e32 v66, v78
	s_nop 0
	v_pk_mul_f32 v[66:67], v[70:71], v[66:67]
	s_nop 0
	v_pk_mul_f32 v[70:71], v[64:65], v[66:67]
	v_cvt_pk_bf16_f32 v66, v68, v69
	v_mad_i64_i32 v[68:69], s[0:1], v80, s44, v[112:113]
	v_cvt_pk_bf16_f32 v64, v72, v73
	v_cvt_pk_bf16_f32 v65, v74, v75
	v_cvt_pk_bf16_f32 v67, v70, v71
	v_lshl_add_u64 v[68:69], v[68:69], 0, v[114:115]
	global_store_dwordx4 v[68:69], v[64:67], off
	s_nop 0
	v_add_u32_e32 v70, 0x80, v144
	s_nop 0
	v_fmamk_f32 v64, v251, 0x3a800000, v158
	v_mul_f32_e32 v65, 0x4b800000, v64
	v_cmp_gt_f32_e32 vcc, s43, v64
	s_nop 1
	v_cndmask_b32_e32 v64, v64, v65, vcc
	v_rsq_f32_e32 v64, v64
	s_nop 0
	v_mul_f32_e32 v65, 0x45800000, v64
	v_cndmask_b32_e32 v64, v64, v65, vcc
	v_pk_mul_f32 v[60:61], v[60:61], v[64:65] op_sel_hi:[1,0]
; DI unsigned pk2(float lo, float hi) { f32x2_t v = {lo, hi}; bf16x2_t b = __builtin_convertvector(v, bf16x2_t); return __builtin_bit_cast(unsigned, b); }
; DI float sigmoidf_(float x) { return 1.0f / (1.0f + __expf(-x)); }
;     DI void operator()(AccRef acc, const Unit& u, int wr, int wc, int fr, int fq) const {
;     ...
;         for (int ai = 0; ai < 2; ++ai)
; #pragma unroll
;             for (int m = 0; m < 4; ++m) {
;                 const int row = row0 + ai * HALF + m * 16; const float rs = rsqrtf(SS1[row] * (1.0f / DM) + EPSN);
;                 float h[8];
; #pragma unroll
;                 for (int n = 0; n < 2; ++n)
; #pragma unroll
;                     for (int e = 0; e < 4; ++e) { const float g = acc[ai][0][m][n][e] * rs, up = acc[ai][1][m][n][e] * rs; h[4 * n + e] = g * sigmoidf_(g) * up; }
;                 u32x4 w; w.x = pk2(h[0], h[1]); w.y = pk2(h[2], h[3]); w.z = pk2(h[4], h[5]); w.w = pk2(h[6], h[7]);
;                 *(u32x4*)(H + (size_t)row * DFF + col0) = w;
;             }
	s_nop 0
	v_mul_f32_e32 v65, 0xbfb8aa3b, v60
	v_exp_f32_e32 v66, v65
	v_mul_f32_e32 v65, 0xbfb8aa3b, v61
	v_exp_f32_e32 v67, v65
	s_nop 0
	v_pk_add_f32 v[66:67], v[66:67], 1.0 op_sel_hi:[1,0]
	s_nop 0
	v_pk_mul_f32 v[56:57], v[56:57], v[64:65] op_sel_hi:[1,0]
	v_rcp_f32_e32 v67, v67
	v_pk_mul_f32 v[62:63], v[62:63], v[64:65] op_sel_hi:[1,0]
	v_mul_f32_e32 v68, 0xbfb8aa3b, v62
	v_mul_f32_e32 v69, 0xbfb8aa3b, v63
	v_exp_f32_e32 v68, v68
	v_exp_f32_e32 v69, v69
	v_rcp_f32_e32 v66, v66
	s_nop 0
	v_pk_mul_f32 v[60:61], v[60:61], v[66:67]
	v_pk_add_f32 v[68:69], v[68:69], 1.0 op_sel_hi:[1,0]
	s_nop 0
	v_pk_mul_f32 v[56:57], v[56:57], v[60:61]
	v_pk_mul_f32 v[58:59], v[58:59], v[64:65] op_sel_hi:[1,0]
	v_rcp_f32_e32 v61, v69
	v_pk_mul_f32 v[52:53], v[52:53], v[64:65] op_sel_hi:[1,0]
	v_mul_f32_e32 v65, 0xbfb8aa3b, v52
	v_exp_f32_e32 v66, v65
	v_mul_f32_e32 v65, 0xbfb8aa3b, v53
	v_exp_f32_e32 v67, v65
	v_rcp_f32_e32 v60, v68
	s_nop 0
	v_pk_mul_f32 v[60:61], v[62:63], v[60:61]
	v_pk_add_f32 v[66:67], v[66:67], 1.0 op_sel_hi:[1,0]
	v_pk_mul_f32 v[58:59], v[58:59], v[60:61]
	v_pk_mul_f32 v[48:49], v[48:49], v[64:65] op_sel_hi:[1,0]
	v_rcp_f32_e32 v61, v67
	v_pk_mul_f32 v[54:55], v[54:55], v[64:65] op_sel_hi:[1,0]
	v_mul_f32_e32 v62, 0xbfb8aa3b, v54
	v_mul_f32_e32 v63, 0xbfb8aa3b, v55
	v_exp_f32_e32 v62, v62
	v_exp_f32_e32 v63, v63
	v_rcp_f32_e32 v60, v66
	s_nop 0
	v_pk_mul_f32 v[52:53], v[52:53], v[60:61]
	v_pk_add_f32 v[62:63], v[62:63], 1.0 op_sel_hi:[1,0]
	v_pk_mul_f32 v[52:53], v[48:49], v[52:53]
	v_pk_mul_f32 v[48:49], v[50:51], v[64:65] op_sel_hi:[1,0]
	v_rcp_f32_e32 v51, v63
	v_rcp_f32_e32 v50, v62
	s_nop 0
	v_pk_mul_f32 v[50:51], v[54:55], v[50:51]
	s_nop 0
	v_pk_mul_f32 v[54:55], v[48:49], v[50:51]
	v_cvt_pk_bf16_f32 v50, v52, v53
	v_mad_i64_i32 v[52:53], s[0:1], v70, s44, v[112:113]
	v_cvt_pk_bf16_f32 v48, v56, v57
	v_cvt_pk_bf16_f32 v49, v58, v59
	v_cvt_pk_bf16_f32 v51, v54, v55
	v_lshl_add_u64 v[52:53], v[52:53], 0, v[114:115]
	global_store_dwordx4 v[52:53], v[48:51], off
	s_nop 0
	v_add_u32_e32 v54, 0x90, v144
	s_nop 0
	v_fmamk_f32 v48, v252, 0x3a800000, v158
	v_mul_f32_e32 v49, 0x4b800000, v48
	v_cmp_gt_f32_e32 vcc, s43, v48
	s_nop 1
	v_cndmask_b32_e32 v48, v48, v49, vcc
	v_rsq_f32_e32 v48, v48
	s_nop 0
	v_mul_f32_e32 v49, 0x45800000, v48
	v_cndmask_b32_e32 v48, v48, v49, vcc
	v_pk_mul_f32 v[44:45], v[44:45], v[48:49] op_sel_hi:[1,0]
	s_nop 0
	v_mul_f32_e32 v49, 0xbfb8aa3b, v44
	v_exp_f32_e32 v50, v49
	v_mul_f32_e32 v49, 0xbfb8aa3b, v45
	v_exp_f32_e32 v51, v49
	s_nop 0
	v_pk_add_f32 v[50:51], v[50:51], 1.0 op_sel_hi:[1,0]
	s_nop 0
	v_pk_mul_f32 v[40:41], v[40:41], v[48:49] op_sel_hi:[1,0]
	v_rcp_f32_e32 v51, v51
	v_pk_mul_f32 v[46:47], v[46:47], v[48:49] op_sel_hi:[1,0]
	v_mul_f32_e32 v52, 0xbfb8aa3b, v46
	v_mul_f32_e32 v53, 0xbfb8aa3b, v47
	v_exp_f32_e32 v52, v52
	v_exp_f32_e32 v53, v53
	v_rcp_f32_e32 v50, v50
	s_nop 0
	v_pk_mul_f32 v[44:45], v[44:45], v[50:51]
	v_pk_add_f32 v[52:53], v[52:53], 1.0 op_sel_hi:[1,0]
	s_nop 0
	v_pk_mul_f32 v[40:41], v[40:41], v[44:45]
	v_pk_mul_f32 v[42:43], v[42:43], v[48:49] op_sel_hi:[1,0]
	v_rcp_f32_e32 v45, v53
	v_pk_mul_f32 v[36:37], v[36:37], v[48:49] op_sel_hi:[1,0]
	v_mul_f32_e32 v49, 0xbfb8aa3b, v36
	v_exp_f32_e32 v50, v49
	v_mul_f32_e32 v49, 0xbfb8aa3b, v37
	v_exp_f32_e32 v51, v49
	v_rcp_f32_e32 v44, v52
	s_nop 0
	v_pk_mul_f32 v[44:45], v[46:47], v[44:45]
	v_pk_add_f32 v[50:51], v[50:51], 1.0 op_sel_hi:[1,0]
	v_pk_mul_f32 v[42:43], v[42:43], v[44:45]
	v_pk_mul_f32 v[32:33], v[32:33], v[48:49] op_sel_hi:[1,0]
	v_rcp_f32_e32 v45, v51
	v_pk_mul_f32 v[38:39], v[38:39], v[48:49] op_sel_hi:[1,0]
	v_mul_f32_e32 v46, 0xbfb8aa3b, v38
	v_mul_f32_e32 v47, 0xbfb8aa3b, v39
	v_exp_f32_e32 v46, v46
	v_exp_f32_e32 v47, v47
	v_rcp_f32_e32 v44, v50
	s_nop 0
	v_pk_mul_f32 v[36:37], v[36:37], v[44:45]
	v_pk_add_f32 v[46:47], v[46:47], 1.0 op_sel_hi:[1,0]
	v_pk_mul_f32 v[36:37], v[32:33], v[36:37]
	v_pk_mul_f32 v[32:33], v[34:35], v[48:49] op_sel_hi:[1,0]
	v_rcp_f32_e32 v35, v47
	v_rcp_f32_e32 v34, v46
	s_nop 0
	v_pk_mul_f32 v[34:35], v[38:39], v[34:35]
	s_nop 0
	v_pk_mul_f32 v[38:39], v[32:33], v[34:35]
	v_cvt_pk_bf16_f32 v34, v36, v37
	v_mad_i64_i32 v[36:37], s[0:1], v54, s44, v[112:113]
	v_cvt_pk_bf16_f32 v32, v40, v41
	v_cvt_pk_bf16_f32 v33, v42, v43
	v_cvt_pk_bf16_f32 v35, v38, v39
	v_lshl_add_u64 v[36:37], v[36:37], 0, v[114:115]
	global_store_dwordx4 v[36:37], v[32:35], off
	s_nop 0
	v_add_u32_e32 v38, 0xa0, v144
	s_nop 0
	v_fmamk_f32 v32, v253, 0x3a800000, v158
	v_mul_f32_e32 v33, 0x4b800000, v32
	v_cmp_gt_f32_e32 vcc, s43, v32
	s_nop 1
	v_cndmask_b32_e32 v32, v32, v33, vcc
	v_rsq_f32_e32 v32, v32
; DI unsigned pk2(float lo, float hi) { f32x2_t v = {lo, hi}; bf16x2_t b = __builtin_convertvector(v, bf16x2_t); return __builtin_bit_cast(unsigned, b); }
; DI float sigmoidf_(float x) { return 1.0f / (1.0f + __expf(-x)); }
;     DI void operator()(AccRef acc, const Unit& u, int wr, int wc, int fr, int fq) const {
;     ...
;         for (int ai = 0; ai < 2; ++ai)
; #pragma unroll
;             for (int m = 0; m < 4; ++m) {
;                 const int row = row0 + ai * HALF + m * 16; const float rs = rsqrtf(SS1[row] * (1.0f / DM) + EPSN);
;                 float h[8];
; #pragma unroll
;                 for (int n = 0; n < 2; ++n)
; #pragma unroll
;                     for (int e = 0; e < 4; ++e) { const float g = acc[ai][0][m][n][e] * rs, up = acc[ai][1][m][n][e] * rs; h[4 * n + e] = g * sigmoidf_(g) * up; }
;                 u32x4 w; w.x = pk2(h[0], h[1]); w.y = pk2(h[2], h[3]); w.z = pk2(h[4], h[5]); w.w = pk2(h[6], h[7]);
;                 *(u32x4*)(H + (size_t)row * DFF + col0) = w;
;             }
	s_nop 0
	v_mul_f32_e32 v33, 0x45800000, v32
	v_cndmask_b32_e32 v32, v32, v33, vcc
	v_pk_mul_f32 v[28:29], v[28:29], v[32:33] op_sel_hi:[1,0]
	s_nop 0
	v_mul_f32_e32 v33, 0xbfb8aa3b, v28
	v_exp_f32_e32 v34, v33
	v_mul_f32_e32 v33, 0xbfb8aa3b, v29
	v_exp_f32_e32 v35, v33
	s_nop 0
	v_pk_add_f32 v[34:35], v[34:35], 1.0 op_sel_hi:[1,0]
	s_nop 0
	v_pk_mul_f32 v[24:25], v[24:25], v[32:33] op_sel_hi:[1,0]
	v_rcp_f32_e32 v35, v35
	v_pk_mul_f32 v[30:31], v[30:31], v[32:33] op_sel_hi:[1,0]
	v_mul_f32_e32 v36, 0xbfb8aa3b, v30
	v_mul_f32_e32 v37, 0xbfb8aa3b, v31
	v_exp_f32_e32 v36, v36
	v_exp_f32_e32 v37, v37
	v_rcp_f32_e32 v34, v34
	s_nop 0
	v_pk_mul_f32 v[28:29], v[28:29], v[34:35]
	v_pk_add_f32 v[36:37], v[36:37], 1.0 op_sel_hi:[1,0]
	s_nop 0
	v_pk_mul_f32 v[24:25], v[24:25], v[28:29]
	v_pk_mul_f32 v[26:27], v[26:27], v[32:33] op_sel_hi:[1,0]
	v_rcp_f32_e32 v29, v37
	v_pk_mul_f32 v[20:21], v[20:21], v[32:33] op_sel_hi:[1,0]
	v_mul_f32_e32 v33, 0xbfb8aa3b, v20
	v_exp_f32_e32 v34, v33
	v_mul_f32_e32 v33, 0xbfb8aa3b, v21
	v_exp_f32_e32 v35, v33
	v_rcp_f32_e32 v28, v36
	s_nop 0
	v_pk_mul_f32 v[28:29], v[30:31], v[28:29]
	v_pk_add_f32 v[34:35], v[34:35], 1.0 op_sel_hi:[1,0]
	v_pk_mul_f32 v[26:27], v[26:27], v[28:29]
	v_pk_mul_f32 v[16:17], v[16:17], v[32:33] op_sel_hi:[1,0]
	v_rcp_f32_e32 v29, v35
	v_pk_mul_f32 v[22:23], v[22:23], v[32:33] op_sel_hi:[1,0]
	v_mul_f32_e32 v30, 0xbfb8aa3b, v22
	v_mul_f32_e32 v31, 0xbfb8aa3b, v23
	v_exp_f32_e32 v30, v30
	v_exp_f32_e32 v31, v31
	v_rcp_f32_e32 v28, v34
	s_nop 0
	v_pk_mul_f32 v[20:21], v[20:21], v[28:29]
	v_pk_add_f32 v[30:31], v[30:31], 1.0 op_sel_hi:[1,0]
	v_pk_mul_f32 v[20:21], v[16:17], v[20:21]
	v_pk_mul_f32 v[16:17], v[18:19], v[32:33] op_sel_hi:[1,0]
	v_rcp_f32_e32 v19, v31
	v_rcp_f32_e32 v18, v30
	s_nop 0
	v_pk_mul_f32 v[18:19], v[22:23], v[18:19]
	s_nop 0
	v_pk_mul_f32 v[22:23], v[16:17], v[18:19]
	v_cvt_pk_bf16_f32 v18, v20, v21
	v_mad_i64_i32 v[20:21], s[0:1], v38, s44, v[112:113]
	v_cvt_pk_bf16_f32 v16, v24, v25
	v_cvt_pk_bf16_f32 v17, v26, v27
	v_cvt_pk_bf16_f32 v19, v22, v23
	v_lshl_add_u64 v[20:21], v[20:21], 0, v[114:115]
	global_store_dwordx4 v[20:21], v[16:19], off
	s_nop 0
	v_add_u32_e32 v22, 0xb0, v144
	s_nop 0
	v_fmamk_f32 v16, v254, 0x3a800000, v158
	v_mul_f32_e32 v17, 0x4b800000, v16
	v_cmp_gt_f32_e32 vcc, s43, v16
	s_nop 1
	v_cndmask_b32_e32 v16, v16, v17, vcc
	v_rsq_f32_e32 v16, v16
	s_nop 0
	v_mul_f32_e32 v17, 0x45800000, v16
	v_cndmask_b32_e32 v16, v16, v17, vcc
	v_pk_mul_f32 v[12:13], v[12:13], v[16:17] op_sel_hi:[1,0]
	s_nop 0
	v_mul_f32_e32 v17, 0xbfb8aa3b, v12
	v_exp_f32_e32 v18, v17
	v_mul_f32_e32 v17, 0xbfb8aa3b, v13
	v_exp_f32_e32 v19, v17
	s_nop 0
	v_pk_add_f32 v[18:19], v[18:19], 1.0 op_sel_hi:[1,0]
	s_nop 0
	v_pk_mul_f32 v[8:9], v[8:9], v[16:17] op_sel_hi:[1,0]
	v_rcp_f32_e32 v19, v19
	v_pk_mul_f32 v[14:15], v[14:15], v[16:17] op_sel_hi:[1,0]
	v_mul_f32_e32 v20, 0xbfb8aa3b, v14
	v_mul_f32_e32 v21, 0xbfb8aa3b, v15
	v_exp_f32_e32 v20, v20
	v_exp_f32_e32 v21, v21
	v_rcp_f32_e32 v18, v18
	s_nop 0
	v_pk_mul_f32 v[12:13], v[12:13], v[18:19]
	v_pk_add_f32 v[20:21], v[20:21], 1.0 op_sel_hi:[1,0]
	s_nop 0
	v_pk_mul_f32 v[8:9], v[8:9], v[12:13]
	v_pk_mul_f32 v[10:11], v[10:11], v[16:17] op_sel_hi:[1,0]
	v_rcp_f32_e32 v13, v21
	v_pk_mul_f32 v[4:5], v[4:5], v[16:17] op_sel_hi:[1,0]
	v_mul_f32_e32 v17, 0xbfb8aa3b, v4
	v_exp_f32_e32 v18, v17
	v_mul_f32_e32 v17, 0xbfb8aa3b, v5
	v_exp_f32_e32 v19, v17
	v_rcp_f32_e32 v12, v20
	s_nop 0
	v_pk_mul_f32 v[12:13], v[14:15], v[12:13]
	v_pk_add_f32 v[18:19], v[18:19], 1.0 op_sel_hi:[1,0]
	v_pk_mul_f32 v[10:11], v[10:11], v[12:13]
	v_pk_mul_f32 v[0:1], v[0:1], v[16:17] op_sel_hi:[1,0]
	v_rcp_f32_e32 v13, v19
	v_pk_mul_f32 v[6:7], v[6:7], v[16:17] op_sel_hi:[1,0]
	v_mul_f32_e32 v14, 0xbfb8aa3b, v6
	v_mul_f32_e32 v15, 0xbfb8aa3b, v7
	v_exp_f32_e32 v14, v14
	v_exp_f32_e32 v15, v15
	v_rcp_f32_e32 v12, v18
	s_nop 0
	v_pk_mul_f32 v[4:5], v[4:5], v[12:13]
	v_pk_add_f32 v[14:15], v[14:15], 1.0 op_sel_hi:[1,0]
	v_pk_mul_f32 v[4:5], v[0:1], v[4:5]
	v_pk_mul_f32 v[0:1], v[2:3], v[16:17] op_sel_hi:[1,0]
	v_rcp_f32_e32 v3, v15
	v_rcp_f32_e32 v2, v14
	s_nop 0
	v_pk_mul_f32 v[2:3], v[6:7], v[2:3]
	s_andn2_b64 vcc, exec, s[2:3]
	v_pk_mul_f32 v[6:7], v[0:1], v[2:3]
	v_cvt_pk_bf16_f32 v2, v4, v5
	v_mad_i64_i32 v[4:5], s[0:1], v22, s44, v[112:113]
	v_cvt_pk_bf16_f32 v0, v8, v9
	v_cvt_pk_bf16_f32 v1, v10, v11
	v_cvt_pk_bf16_f32 v3, v6, v7
	v_lshl_add_u64 v[4:5], v[4:5], 0, v[114:115]
	s_mov_b64 s[0:1], -1
	global_store_dwordx4 v[4:5], v[0:3], off
	s_cbranch_vccnz .LBB0_1483
	s_andn2_b64 vcc, exec, s[14:15]
	s_cbranch_vccnz .LBB0_1482
	s_barrier
	s_branch .LBB0_1482

; #define PG8_WAIT_V(n) asm volatile("s_waitcnt vmcnt(" #n ")" ::: "memory")
; #define PG8_BAR __builtin_amdgcn_s_barrier()
; template <class Epi, class Sched, bool ALIGN_EPI = false, bool SP2 = false>
; __device__ __forceinline__ void gemm_phase(PG8_LAS unsigned char* lds, const Gemm g, const Sched& S, const Epi& E) {
;     ...
;     PG8_WAIT_V(0);
;     if constexpr (!ALIGN_EPI) { if (wr == 0) PG8_BAR; }
;     PG8_BAR;
.LBB0_1547:
	s_or_b64 exec, exec, s[2:3]
	s_waitcnt lgkmcnt(0)
	s_barrier
	s_nop 0
	s_nop 0
	s_nop 0
	s_nop 0
	s_nop 0
	s_nop 0
	s_nop 0
	s_nop 0
	s_nop 0
	s_nop 0
	s_nop 0

; #define PG8_STAGE(bufoff, gbase, voff) do { _Pragma("unroll") for (int _i = 0; _i < 2; ++_i) \
;         __builtin_amdgcn_global_load_lds((const unsigned*)((const char*)(gbase) + (voff)[_i]), (PG8_LAS unsigned*)(lds + (bufoff) + ldsw + _i * 8192), 16, 0, 0); } while (0)
; #define PG8_WAIT_V(n) asm volatile("s_waitcnt vmcnt(" #n ")" ::: "memory")
; #define PG8_BAR __builtin_amdgcn_s_barrier()
; template <class Epi, class Sched, bool ALIGN_EPI = false, bool SP2 = false>
; __device__ __forceinline__ void gemm_phase(PG8_LAS unsigned char* lds, const Gemm g, const Sched& S, const Epi& E) {
;     ...
;         PG8_STAGE(PG8_SB(1, 0), cB + kstep, voffB); PG8_STAGE(PG8_SA(1, 0), cA + kstep, voffA); PG8_STAGE(PG8_SB(1, 1), cB + hstep + kstep, voffB);
;         PG8_WAIT_V(6); PG8_BAR;
;     } else {
;         PG8_STAGE(PG8_SB(0, 0), cB, voffB); PG8_STAGE(PG8_SA(0, 0), cA, voffA); PG8_STAGE(PG8_SB(0, 1), cB + hstep, voffB); PG8_STAGE(PG8_SA(0, 1), cA + hstep, voffA);
;         if (wr == 1) PG8_BAR;
;         PG8_WAIT_V(4); PG8_BAR;
;         PG8_STAGE(PG8_SB(1, 0), cB + kstep, voffB); PG8_STAGE(PG8_SA(1, 0), cA + kstep, voffA); PG8_STAGE(PG8_SB(1, 1), cB + hstep + kstep, voffB);
;         PG8_WAIT_V(6); PG8_BAR;
.LBB0_1656:
	s_add_u32 s48, s48, 0x4800000
	s_addc_u32 s49, s49, 0
	s_nop 0
	s_nop 0
	s_nop 0
	s_nop 0
	s_nop 0
	s_nop 0
	s_nop 0
	s_nop 0
	s_nop 0
	s_nop 0
	s_nop 0
	s_nop 0
	s_nop 0
	s_nop 0
	s_nop 0
	s_cmp_lt_i32 s84, 10
	s_cselect_b64 s[2:3], -1, 0
	s_and_b64 s[14:15], s[2:3], s[0:1]
	s_andn2_b64 vcc, exec, s[14:15]
	s_cbranch_vccnz .LBB0_1673
	s_cmpk_gt_i32 s33, 0x57f
	v_readfirstlane_b32 s3, v150
	s_cbranch_scc1 .LBB0_1673
	v_lshrrev_b32_e32 v0, 5, v150
	v_lshrrev_b32_e32 v2, 1, v150
	v_and_b32_e32 v0, 4, v0
	s_waitcnt lgkmcnt(0)
	v_bfe_u32 v1, v150, 2, 2
	v_and_b32_e32 v11, 24, v2
	v_or3_b32 v0, v0, v1, v11
	v_lshlrev_b32_e32 v1, 4, v150
	v_add_u32_e32 v8, 0x2000, v1
	v_lshrrev_b32_e32 v2, 7, v8
	s_movk_i32 s0, 0xe0
	v_and_b32_e32 v4, 32, v150
	v_and_or_b32 v3, v2, s0, v0
	v_bitop3_b32 v9, v1, v4, 48 bitop3:0x6c
	v_and_b32_e32 v10, 64, v150
	v_bfe_u32 v12, v150, 2, 4
	s_movk_i32 s0, 0xf0
	v_or_b32_e32 v1, v9, v10
	v_and_or_b32 v2, v2, s0, v12
	s_add_u32 s34, s82, 0x4000000
	v_lshl_or_b32 v130, v2, 11, v1
	v_lshrrev_b32_e32 v2, 3, v150
	s_movk_i32 s0, 0x60
	s_addc_u32 s35, s83, 0
	v_and_or_b32 v0, v2, s0, v0
	s_movk_i32 s0, 0x70
	s_ashr_i32 s37, s33, 31
	v_lshl_or_b32 v132, v0, 11, v1
	v_and_or_b32 v0, v2, s0, v12
	s_lshr_b32 s0, s37, 29
	s_add_i32 s0, s33, s0
	s_lshr_b32 s9, s3, 6
	s_ashr_i32 s1, s0, 3
	s_and_b32 s0, s0, -8
	s_lshr_b32 s8, s3, 8
	s_lshl_b32 s36, s9, 10
	s_sub_i32 s0, s33, s0
	s_cmp_lt_i32 s0, 0
	s_movk_i32 s38, 0xb1
	s_cselect_b32 s2, s38, 0xb0
	s_mul_i32 s0, s0, s2
	s_add_i32 s0, s0, s1
	s_mul_hi_i32 s1, s0, 0x2e8ba2e9
	s_lshr_b32 s2, s1, 31
	s_ashr_i32 s1, s1, 5
	s_add_i32 s1, s1, s2
	s_lshl_b32 s4, s1, 3
	s_mulk_i32 s1, 0xb0
	s_sub_i32 s0, s0, s1
	s_sext_i32_i16 s1, s0
	s_bfe_u32 s1, s1, 0x3001c
	s_add_i32 s1, s0, s1
	s_sext_i32_i16 s2, s1
	s_and_b32 s1, s1, 0xfff8
	s_sub_i32 s0, s0, s1
	s_sext_i32_i16 s0, s0
	s_lshr_b32 s2, s2, 3
	s_add_i32 s0, s4, s0
	s_ashr_i32 s1, s0, 31
	s_bfe_i64 s[6:7], s[2:3], 0x100000
	s_lshl_b64 s[4:5], s[0:1], 19
	s_lshl_b64 s[6:7], s[6:7], 19
	s_add_u32 s6, s90, s6
	s_addc_u32 s7, s91, s7
	s_add_i32 s39, s36, 0
	s_add_i32 m0, s39, 0x10000
	v_lshl_or_b32 v128, v3, 11, v1
	global_load_lds_dwordx4 v132, s[6:7]
	s_add_i32 m0, s39, 0x12000
	s_add_u32 s10, s6, 0x40000
	global_load_lds_dwordx4 v128, s[6:7]
	s_addc_u32 s11, s7, 0
	s_add_i32 m0, s39, 0x14000
	v_lshl_or_b32 v134, v0, 11, v1
	global_load_lds_dwordx4 v132, s[10:11]
	s_add_i32 m0, s39, 0x16000
	s_add_u32 s4, s34, s4
	s_addc_u32 s5, s35, s5
	s_add_i32 s40, s39, 0x2000
	global_load_lds_dwordx4 v128, s[10:11]
	s_mov_b32 m0, s39
	s_add_u32 s10, s4, 0x40000
	global_load_lds_dwordx4 v134, s[4:5]
	s_mov_b32 m0, s40
	s_addc_u32 s11, s5, 0
	s_add_i32 s41, s39, 0x4000
	global_load_lds_dwordx4 v130, s[4:5]
	s_mov_b32 m0, s41
	s_add_i32 s42, s39, 0x6000
	global_load_lds_dwordx4 v134, s[10:11]
	s_mov_b32 m0, s42
	v_mov_b32_e32 v133, 0
	global_load_lds_dwordx4 v130, s[10:11]
	v_mov_b32_e32 v129, v133
	v_mov_b32_e32 v135, v133
	v_mov_b32_e32 v131, v133
	s_cmp_eq_u32 s8, 1
	s_mov_b32 s43, 0
	v_lshl_add_u64 v[6:7], s[6:7], 0, v[132:133]
	v_lshl_add_u64 v[4:5], s[6:7], 0, v[128:129]
	v_lshl_add_u64 v[0:1], s[4:5], 0, v[134:135]
	s_cselect_b64 s[16:17], -1, 0
	s_cmp_lg_u32 s8, 1
	v_lshl_add_u64 v[2:3], s[4:5], 0, v[130:131]
	s_cbranch_scc1 .LBB0_1660
	s_barrier
.LBB0_1660:
	s_add_u32 s18, s82, 0x30000
	s_addc_u32 s19, s83, 0
	s_lshl_b32 s1, s9, 5
	s_mov_b64 s[20:21], 0x80
	s_and_b32 s9, s1, 0x60
	s_add_i32 m0, s39, 0x18000
	v_lshl_add_u64 v[6:7], v[6:7], 0, s[20:21]
	s_lshl_b32 s22, s8, 13
	s_lshl_b32 s23, s9, 7
	global_load_lds_dwordx4 v[6:7], off
	v_lshl_add_u64 v[4:5], v[4:5], 0, s[20:21]
	s_add_i32 m0, s39, 0x1a000
	s_add_i32 s44, s39, 0x8000
	s_add_i32 s45, s39, 0xa000
	global_load_lds_dwordx4 v[4:5], off
	v_lshl_add_u64 v[0:1], v[0:1], 0, s[20:21]
	s_mov_b32 m0, s44
	s_add_u32 s10, s6, 0x40080
	global_load_lds_dwordx4 v[0:1], off
	v_lshl_add_u64 v[0:1], v[2:3], 0, s[20:21]
	s_mov_b32 m0, s45
	s_addc_u32 s11, s7, 0
	global_load_lds_dwordx4 v[0:1], off
	s_add_i32 m0, s39, 0x1c000
	v_lshl_add_u64 v[0:1], s[10:11], 0, v[132:133]
	global_load_lds_dwordx4 v[0:1], off
	v_lshl_add_u64 v[0:1], s[10:11], 0, v[128:129]
	s_add_i32 m0, s39, 0x1e000
	s_sext_i32_i16 s1, s2
	global_load_lds_dwordx4 v[0:1], off
	s_waitcnt vmcnt(8)
	s_barrier
	v_and_b32_e32 v0, 15, v150
	v_lshlrev_b32_e32 v1, 1, v11
	v_lshlrev_b32_e32 v2, 2, v150
	v_lshlrev_b32_e32 v3, 6, v150
	s_movk_i32 s2, 0x3c0
	v_lshl_or_b32 v149, s8, 6, v0
	v_lshl_or_b32 v0, v0, 6, v1
	v_and_b32_e32 v2, 32, v2
	v_and_or_b32 v1, v3, s2, v1
	v_bitop3_b32 v151, s23, v1, v2 bitop3:0xf6
	v_lshlrev_b32_e32 v1, 8, v150
	v_bitop3_b32 v0, v0, s22, v2 bitop3:0xde
	v_and_b32_e32 v1, 0x38000, v1
	v_lshlrev_b32_e32 v2, 11, v12
	v_or3_b32 v1, v9, v1, v2
	v_add_u32_e32 v136, v1, v10
	v_lshlrev_b32_e32 v1, 4, v8
	s_waitcnt vmcnt(6)
	s_cmpk_lt_u32 s3, 0x100
	v_and_b32_e32 v1, 0x78000, v1
	s_cselect_b64 s[22:23], -1, 0
	v_or3_b32 v1, v9, v1, v2
	s_add_i32 s47, 0, 0x10000
	s_add_i32 s50, 0, 0x14000
	s_ashr_i32 s46, s89, 31
	v_or_b32_e32 v154, s9, v11
	v_mov_b32_e32 v137, v133
	v_add_u32_e32 v138, v1, v10
	v_mov_b32_e32 v139, v133
	v_mov_b64_e32 v[140:141], 0x500
	v_mov_b64_e32 v[142:143], 0x4ff
	v_add_u32_e32 v155, s47, v151
	v_add_u32_e32 v156, s50, v151
	v_add_u32_e32 v157, 0, v0
	v_mov_b32_e32 v158, 0x358637bd
	s_mov_b32 s51, 0x800000
	s_movk_i32 s52, 0x1600
	s_barrier
	s_branch .LBB0_1663

;     __host__ __device__ bool next(int i, Unit& u) const {
;         const long L = (long)i * G + c; if (L >= nwg) return false;
;         int wgid = (int)L; { const int q = nwg / NXCD, r = nwg % NXCD, xcd = wgid % NXCD, off = wgid / NXCD; wgid = (xcd < r ? xcd * (q + 1) : r * (q + 1) + (xcd - r) * q) + off; }
;         const int nig = WGM * nN, gid = wgid / nig, fm = gid * WGM, gsz = (nM - fm) < WGM ? (nM - fm) : WGM;
;         u.pm = fm + ((wgid % nig) % gsz); u.pn = (wgid % nig) / gsz; return true;
;     }
.LBB0_1663:
	s_add_i32 s43, s43, 1
	s_mul_i32 s2, s43, s46
	s_mul_hi_u32 s3, s43, s89
	s_add_i32 s3, s3, s2
	s_mul_i32 s2, s43, s89
	s_add_u32 s8, s2, s33
	s_addc_u32 s9, s3, s37
	v_cmp_gt_i64_e32 vcc, s[8:9], v[142:143]
	v_cmp_lt_i64_e64 s[2:3], s[8:9], v[140:141]
	s_cbranch_vccnz .LBB0_1665
	s_ashr_i32 s9, s8, 31
	s_lshr_b32 s9, s9, 29
	s_add_i32 s9, s8, s9
	s_ashr_i32 s10, s9, 3
	s_and_b32 s9, s9, -8
	s_sub_i32 s8, s8, s9
	s_cmp_lt_i32 s8, 0
	s_cselect_b32 s9, s38, 0xb0
	s_mul_i32 s8, s8, s9
	s_add_i32 s8, s8, s10
	s_cmpk_lt_i32 s10, 0x98
	s_cbranch_scc1 .Lp9_dec_done
	s_and_b32 s98, s33, 7
	s_sub_i32 s99, s98, 2
	s_cmp_gt_u32 s99, 3
	s_cbranch_scc1 .Lp9_dec_done
	s_lshr_b32 s98, s99, 1
	s_and_b32 s99, s99, 1
	s_lshl_b32 s99, s99, 3
	s_add_i32 s99, s99, s10
	s_add_i32 s99, s99, 8
	s_mul_i32 s8, s98, 0xb0
	s_add_i32 s8, s8, s99
.Lp9_dec_done:
	s_mul_hi_i32 s9, s8, 0x2e8ba2e9
	s_lshr_b32 s10, s9, 31
	s_ashr_i32 s9, s9, 5
	s_add_i32 s9, s9, s10
	s_lshl_b32 s10, s9, 3
	s_sub_i32 s11, 64, s10
	s_min_i32 s11, s11, 8
	s_abs_i32 s24, s11
	v_cvt_f32_u32_e32 v0, s24
	s_sub_i32 s26, 0, s24
	s_mulk_i32 s9, 0xb0
	s_sub_i32 s8, s8, s9
	v_rcp_iflag_f32_e32 v0, v0
	s_abs_i32 s9, s8
	s_xor_b32 s25, s8, s11
	s_ashr_i32 s25, s25, 31
	v_mul_f32_e32 v0, 0x4f7ffffe, v0
	v_cvt_u32_f32_e32 v0, v0
	s_nop 0
	v_readfirstlane_b32 s27, v0
	s_mul_i32 s26, s26, s27
	s_mul_hi_u32 s26, s27, s26
	s_add_i32 s27, s27, s26
	s_mul_hi_u32 s26, s9, s27
	s_mul_i32 s27, s26, s24
	s_sub_i32 s9, s9, s27
	s_add_i32 s28, s26, 1
	s_sub_i32 s27, s9, s24
	s_cmp_ge_u32 s9, s24
	s_cselect_b32 s26, s28, s26
	s_cselect_b32 s9, s27, s9
	s_add_i32 s27, s26, 1
	s_cmp_ge_u32 s9, s24
	s_cselect_b32 s9, s27, s26
	s_xor_b32 s9, s9, s25
	s_sub_i32 s24, s9, s25
	s_mul_i32 s9, s24, s11
	s_sub_i32 s8, s8, s9
	s_add_i32 s26, s10, s8
